# attention: radix-select top-16 block ranking, next-tile prefetch at top of deferred-max step, static prio for waves 4-7
# speedup vs baseline: 1.0126x; 1.0126x over previous
; #define LAS __attribute__((address_space(3)))
; __device__ __forceinline__ void attn_item(const bf16_t* Q, const bf16_t* KV, const bf16_t* KC, const bf16_t* VCT, const float* NG, bf16_t* OATT,
;                                           int bg, int tb, LAS unsigned char* lds) {
;     int tid = threadIdx.x; asm volatile("" : "+v"(tid));
;     const int w = __builtin_amdgcn_readfirstlane(tid >> 6), lane = tid & 63, r = w >> 1, qh = w & 1; int ql = lane & 15, g = lane >> 4;
;     asm volatile("" : "+v"(ql), "+v"(g));
;     const int b = bg >> 2, gk = bg & 3, h = gk * 4 + r;
;     int qq[2], t[2], row[2];
;     bf16x8 qf[2][4];
; #pragma unroll
;     for (int gp = 0; gp < 2; ++gp) {
;         qq[gp] = 32 * qh + 16 * gp + ql; t[gp] = 64 * tb + qq[gp]; row[gp] = b * SEQ + t[gp];
; #pragma unroll
;         for (int kc = 0; kc < 4; ++kc) qf[gp][kc] = *(const bf16x8*)(Q + (size_t)row[gp] * DM + h * 128 + kc * 32 + g * 8);
;     }
;     if (tb >= 16) { LAS u32x4* z = (LAS u32x4*)(lds + IMP_OFF);
; #pragma unroll
;       for (int i = 0; i < 8; ++i) z[tid + i * 512] = (u32x4){0u, 0u, 0u, 0u}; }
.LBB0_957:
	s_lshr_b32 s0, s72, 1
	s_or_b32 s36, s0, s95
	s_and_b32 s0, s72, 1
	s_cmp_lt_u32 s72, 2
	s_cselect_b32 s1, s39, s60
	s_sub_i32 s6, 63, s1
	s_cmp_eq_u32 s0, 0
	v_mov_b32_e32 v225, v226
	s_cselect_b32 s0, s6, s1
	s_lshl_b32 s6, s36, 2
	v_readfirstlane_b32 s14, v225
	s_ashr_i32 s1, s14, 6
	s_cmp_ge_i32 s1, 4
	s_cbranch_scc0 .Lattn_prio_done
	s_setprio 1
.Lattn_prio_done:
	s_ashr_i32 s15, s14, 7
	s_and_b32 s6, s6, 12
	s_add_i32 s17, s15, s6
	s_lshl_b32 s6, s1, 5
	v_and_b32_e32 v211, 15, v225
	v_bfe_u32 v220, v225, 4, 2
	s_and_b32 s84, s6, 32
	s_lshl_b32 s6, s17, 7
	v_add_u32_e32 v218, s84, v211
	s_lshl_b32 s85, s0, 6
	s_ashr_i32 s7, s6, 31
	v_add_u32_e32 v219, 16, v218
	s_lshl_b64 s[8:9], s[6:7], 1
	v_add_u32_e32 v216, s85, v218
	v_add_u32_e32 v215, s85, v219
	s_add_u32 s6, s78, s8
	v_lshlrev_b32_e32 v148, 3, v220
	v_add_u32_e32 v162, s61, v216
	v_add_u32_e32 v158, s61, v215
	s_addc_u32 s7, s79, s9
	v_ashrrev_i32_e32 v149, 31, v148
	v_ashrrev_i32_e32 v163, 31, v162
	v_ashrrev_i32_e32 v159, 31, v158
	v_lshl_add_u64 v[2:3], v[148:149], 1, s[6:7]
	v_lshlrev_b64 v[160:161], 12, v[162:163]
	v_lshlrev_b64 v[154:155], 12, v[158:159]
	v_lshl_add_u64 v[16:17], v[2:3], 0, v[160:161]
	v_lshl_add_u64 v[2:3], v[2:3], 0, v[154:155]
	global_load_dwordx4 v[4:7], v[16:17], off
	global_load_dwordx4 v[8:11], v[16:17], off offset:64
	global_load_dwordx4 v[12:15], v[16:17], off offset:128
	s_nop 0
	global_load_dwordx4 v[16:19], v[16:17], off offset:192
	s_nop 0
	global_load_dwordx4 v[20:23], v[2:3], off
	global_load_dwordx4 v[24:27], v[2:3], off offset:64
	global_load_dwordx4 v[28:31], v[2:3], off offset:128
	global_load_dwordx4 v[32:35], v[2:3], off offset:192
	s_cmp_gt_i32 s0, 15
	s_cselect_b64 s[6:7], -1, 0
	s_cmp_lt_i32 s0, 16
	s_cbranch_scc1 .LBB0_959
	v_lshl_add_u32 v0, v225, 4, 0
	v_add_u32_e32 v0, 0x11800, v0
	ds_write_b128 v0, v[240:243]
	ds_write_b128 v0, v[240:243] offset:8192
	ds_write_b128 v0, v[240:243] offset:16384
	ds_write_b128 v0, v[240:243] offset:24576
	ds_write_b128 v0, v[240:243] offset:32768
	ds_write_b128 v0, v[240:243] offset:40960
	ds_write_b128 v0, v[240:243] offset:49152
	ds_write_b128 v0, v[240:243] offset:57344

; #define LAS __attribute__((address_space(3)))
; __device__ __forceinline__ void attn_item(const bf16_t* Q, const bf16_t* KV, const bf16_t* KC, const bf16_t* VCT, const float* NG, bf16_t* OATT,
;                                           int bg, int tb, LAS unsigned char* lds) {
;     ...
; #pragma unroll 1
;         for (int i = 0; i < 8; ++i) {
;             const int q2 = 8 * w + i;
;             const LAS float* ip = (const LAS float*)(lds + IMP_OFF) + q2 * 64 + lane;
;             float v = ((ip[0] + ip[64 * 64]) + ip[2 * 64 * 64]) + ip[3 * 64 * 64];
;             const bool valid = lane <= tb, forced = (lane == 0) || (lane == tb) || (lane == tb - 1);
;             v = valid ? (forced ? __builtin_inff() : v) : -__builtin_inff();
;             int rank = 0;
; #pragma unroll 8
;             for (int mm = 0; mm < 64; ++mm) { const float vm = __builtin_bit_cast(float, __builtin_amdgcn_readlane(__builtin_bit_cast(int, v), mm)); rank += (vm > v || (vm == v && mm < lane)) ? 1 : 0; }
;             const unsigned long long mask = __ballot(rank < 16);
;             if (lane == 0) *(LAS unsigned long long*)(lds + SELM_OFF + q2 * 8) = mask;
;         }
;     }
.LBB0_993:
	s_add_i32 s6, 0, 0x11800
	v_lshl_add_u32 v3, v72, 2, s6
	v_cmp_eq_u32_e64 s[6:7], 0, v72
	v_cmp_eq_u32_e64 s[8:9], s0, v72
	s_or_b64 s[10:11], s[6:7], s[8:9]
	s_add_i32 s8, s0, -1
	v_cmp_eq_u32_e64 s[8:9], s8, v72
	s_lshl_b32 s1, s1, 3
	v_cmp_lt_i32_e32 vcc, s0, v72
	s_mov_b32 s16, 0
	s_or_b64 s[8:9], s[10:11], s[8:9]
	s_waitcnt vmcnt(0)
.Lrank_pair:
	s_add_i32 s17, s16, s1
	v_lshl_add_u32 v38, s17, 8, v3
	ds_read2st64_b32 v[36:37], v38 offset1:64
	ds_read2st64_b32 v[40:41], v38 offset0:128 offset1:192
	v_add_u32_e32 v39, 0x100, v38
	ds_read2st64_b32 v[42:43], v39 offset1:64
	ds_read2st64_b32 v[44:45], v39 offset0:128 offset1:192
	s_mov_b32 s20, 0
	s_mov_b32 s21, 0
	s_mov_b32 s18, 0x40000000
	s_waitcnt lgkmcnt(2)
	v_add_f32_e32 v36, v36, v37
	v_add_f32_e32 v36, v36, v40
	v_add_f32_e32 v36, v36, v41
	s_waitcnt lgkmcnt(0)
	v_add_f32_e32 v42, v42, v43
	v_add_f32_e32 v42, v42, v44
	v_add_f32_e32 v42, v42, v45
	v_cndmask_b32_e64 v36, v36, v234, s[8:9]
	v_cndmask_b32_e64 v42, v42, v234, s[8:9]
	v_add_u32_e32 v46, 1, v36
	v_add_u32_e32 v47, 1, v42
	v_cndmask_b32_e64 v46, v46, 0, vcc
	v_cndmask_b32_e64 v47, v47, 0, vcc
.Lrank_bit:
	s_or_b32 s22, s20, s18
	s_or_b32 s23, s21, s18
	v_cmp_le_u32_e64 s[24:25], s22, v46
	v_cmp_le_u32_e64 s[26:27], s23, v47
	s_lshr_b32 s18, s18, 1
	s_nop 0
	s_bcnt1_i32_b64 s10, s[24:25]
	s_bcnt1_i32_b64 s11, s[26:27]
	s_cmp_ge_u32 s10, 16
	s_cselect_b32 s20, s22, s20
	s_cmp_ge_u32 s11, 16
	s_cselect_b32 s21, s23, s21
	s_cmp_lg_u32 s18, 0
	s_cbranch_scc1 .Lrank_bit
	v_cmp_lt_u32_e64 s[24:25], s20, v46
	v_cmp_eq_u32_e64 s[12:13], s20, v46
	v_cmp_lt_u32_e64 s[26:27], s21, v47
	v_cmp_eq_u32_e64 s[14:15], s21, v47
	s_nop 1
	s_bcnt1_i32_b64 s10, s[24:25]
	s_bcnt1_i32_b64 s11, s[26:27]
	s_sub_i32 s10, 16, s10
	s_sub_i32 s11, 16, s11
	v_mbcnt_lo_u32_b32 v40, s12, 0
	v_mbcnt_hi_u32_b32 v40, s13, v40
	v_mbcnt_lo_u32_b32 v41, s14, 0
	v_mbcnt_hi_u32_b32 v41, s15, v41
	v_cmp_gt_u32_e64 s[22:23], s10, v40
	v_cmp_gt_u32_e64 s[18:19], s11, v41
	s_nop 1
	s_and_b64 s[12:13], s[12:13], s[22:23]
	s_and_b64 s[14:15], s[14:15], s[18:19]
	s_or_b64 s[12:13], s[12:13], s[24:25]
	s_or_b64 s[14:15], s[14:15], s[26:27]
	s_lshl_b32 s10, s17, 3
	s_add_i32 s10, s10, 0x21800
	v_mov_b32_e32 v36, s10
	v_mov_b64_e32 v[38:39], s[12:13]
	v_mov_b64_e32 v[40:41], s[14:15]
	s_and_saveexec_b64 s[10:11], s[6:7]
	ds_write_b64 v36, v[38:39]
	ds_write_b64 v36, v[40:41] offset:8
	s_or_b64 exec, exec, s[10:11]
	s_add_i32 s16, s16, 2
	s_cmp_eq_u32 s16, 8
	s_cbranch_scc0 .Lrank_pair

; #define LAS __attribute__((address_space(3)))
; #pragma unroll
;     for (int sub = 0; sub < 4; ++sub) { s[0][sub] = (f32x4){init0, init0, init0, init0}; s[1][sub] = (f32x4){init1, init1, init1, init1}; }
; #pragma unroll
;     for (int kc = 0; kc < 4; ++kc) {
;         bf16x8 kf[4];
; #pragma unroll
;         for (int sub = 0; sub < 4; ++sub) kf[sub] = *(const LAS bf16x8*)(buf + (16 * sub + ql) * KT_PITCH + kc * 64 + g * 16);
; #pragma unroll
;         for (int sub = 0; sub < 4; ++sub) {
;             s[0][sub] = __builtin_amdgcn_mfma_f32_16x16x32_bf16(kf[sub], qf[0][kc], s[0][sub], 0, 0, 0);
;             s[1][sub] = __builtin_amdgcn_mfma_f32_16x16x32_bf16(kf[sub], qf[1][kc], s[1][sub], 0, 0, 0);
;         }
;         if (kc & 1) asm volatile("" ::: "memory");
;     }
; }
; template <int MODE, bool DEFER> ...
;     ...
;     if (DEFER) qk_tile2(s, qf, buf, ql, g, take[0] ? -mrun[0] : -__builtin_inff(), take[1] ? -mrun[1] : -__builtin_inff());
;     else qk_tile2(s, qf, buf, ql, g);
;     if (tile < tile_hi) stage_load<true, true>(R, Kg, VTg, vpitch, (tile + 1) * 64, tid);
;     u32x4 pk[2][2];
;     if (DEFER) {
;         float m0 = local_max16(s[0]), m1 = local_max16(s[1]);
;         if (__any(m0 > DEFER_THRESH || m1 > DEFER_THRESH)) {
.LBB0_1008:
	s_bitcmp1_b32 s1, 0
	s_cselect_b32 s7, 0x8c00, 0
	s_add_i32 s11, s7, 0
	s_lshl_b64 s[12:13], 1, s1
	s_ashr_i32 s7, s6, 31
	v_add_u32_e32 v44, s6, v152
	v_ashrrev_i32_e32 v45, 31, v44
	v_lshlrev_b64 v[44:45], 8, v[44:45]
	v_lshl_add_u64 v[44:45], v[176:177], 0, v[44:45]
	global_load_dwordx4 v[44:47], v[44:45], off
	v_lshl_add_u64 v[48:49], s[6:7], 1, v[178:179]
	v_add_u32_e32 v36, s6, v150
	v_ashrrev_i32_e32 v37, 31, v36
	v_lshlrev_b64 v[36:37], 8, v[36:37]
	v_lshl_add_u64 v[36:37], v[176:177], 0, v[36:37]
	global_load_dwordx4 v[36:39], v[36:37], off
	v_lshl_add_u64 v[40:41], v[48:49], 0, v[164:165]
	v_lshl_add_u64 v[48:49], v[48:49], 0, v[166:167]
	global_load_dwordx4 v[40:43], v[40:41], off
	global_load_dwordx4 v[48:51], v[48:49], off
	v_add3_u32 v3, s11, v149, v201
	v_and_b32_e32 v245, s13, v175
	v_and_b32_e32 v244, s12, v174
	ds_read_b128 v[188:191], v3
	ds_read_b128 v[196:199], v3 offset:4352
	ds_read_b128 v[116:119], v3 offset:8704
	ds_read_b128 v[120:123], v3 offset:13056
	v_and_b32_e32 v247, s13, v173
	v_and_b32_e32 v246, s12, v172
	v_cmp_ne_u64_e32 vcc, 0, v[244:245]
	s_nop 0
	s_nop 0
	v_cndmask_b32_e64 v244, v235, -v170, vcc
	v_cmp_ne_u64_e32 vcc, 0, v[246:247]
	v_mov_b32_e32 v245, v244
	v_mov_b32_e32 v246, v244
	v_cndmask_b32_e64 v248, v235, -v171, vcc
	v_mov_b32_e32 v247, v244
	v_mov_b32_e32 v249, v248
	v_mov_b32_e32 v250, v248
	v_mov_b32_e32 v251, v248
	s_waitcnt lgkmcnt(3)
	v_mfma_f32_16x16x32_bf16 v[124:127], v[188:191], v[4:7], v[244:247]
	v_mfma_f32_16x16x32_bf16 v[188:191], v[188:191], v[20:23], v[248:251]
	s_waitcnt lgkmcnt(2)
	v_mfma_f32_16x16x32_bf16 v[128:131], v[196:199], v[4:7], v[244:247]
	v_mfma_f32_16x16x32_bf16 v[196:199], v[196:199], v[20:23], v[248:251]
	s_waitcnt lgkmcnt(1)
	v_mfma_f32_16x16x32_bf16 v[132:135], v[116:119], v[4:7], v[244:247]
	v_mfma_f32_16x16x32_bf16 v[116:119], v[116:119], v[20:23], v[248:251]
	s_waitcnt lgkmcnt(0)
	v_mfma_f32_16x16x32_bf16 v[244:247], v[120:123], v[4:7], v[244:247]
	v_mfma_f32_16x16x32_bf16 v[248:251], v[120:123], v[20:23], v[248:251]
	ds_read_b128 v[120:123], v3 offset:13120
	ds_read_b128 v[136:139], v3 offset:8768
	ds_read_b128 v[140:143], v3 offset:4416
	ds_read_b128 v[144:147], v3 offset:64
	s_waitcnt lgkmcnt(0)
	v_mfma_f32_16x16x32_bf16 v[124:127], v[144:147], v[8:11], v[124:127]
	v_mfma_f32_16x16x32_bf16 v[188:191], v[144:147], v[24:27], v[188:191]
	v_mfma_f32_16x16x32_bf16 v[128:131], v[140:143], v[8:11], v[128:131]
	v_mfma_f32_16x16x32_bf16 v[196:199], v[140:143], v[24:27], v[196:199]
	v_mfma_f32_16x16x32_bf16 v[132:135], v[136:139], v[8:11], v[132:135]
	v_mfma_f32_16x16x32_bf16 v[116:119], v[136:139], v[24:27], v[116:119]
	v_mfma_f32_16x16x32_bf16 v[244:247], v[120:123], v[8:11], v[244:247]
	v_mfma_f32_16x16x32_bf16 v[248:251], v[120:123], v[24:27], v[248:251]
	ds_read_b128 v[120:123], v3 offset:128
	ds_read_b128 v[136:139], v3 offset:4480
	ds_read_b128 v[140:143], v3 offset:8832
	ds_read_b128 v[144:147], v3 offset:13184
	s_waitcnt lgkmcnt(3)
	v_mfma_f32_16x16x32_bf16 v[124:127], v[120:123], v[12:15], v[124:127]
	v_mfma_f32_16x16x32_bf16 v[188:191], v[120:123], v[28:31], v[188:191]
	s_waitcnt lgkmcnt(2)
	v_mfma_f32_16x16x32_bf16 v[120:123], v[136:139], v[12:15], v[128:131]
	v_mfma_f32_16x16x32_bf16 v[196:199], v[136:139], v[28:31], v[196:199]
	ds_read_b128 v[180:183], v3 offset:13248
	ds_read_b128 v[184:187], v3 offset:8896
	ds_read_b128 v[136:139], v3 offset:4544
	ds_read_b128 v[128:131], v3 offset:192
	s_waitcnt lgkmcnt(5)
	v_mfma_f32_16x16x32_bf16 v[132:135], v[140:143], v[12:15], v[132:135]
	s_waitcnt lgkmcnt(4)
	v_mfma_f32_16x16x32_bf16 v[244:247], v[144:147], v[12:15], v[244:247]
	v_mfma_f32_16x16x32_bf16 v[116:119], v[140:143], v[28:31], v[116:119]
	v_mfma_f32_16x16x32_bf16 v[248:251], v[144:147], v[28:31], v[248:251]
	s_waitcnt lgkmcnt(0)
	v_mfma_f32_16x16x32_bf16 v[144:147], v[128:131], v[16:19], v[124:127]
	v_max3_f32 v3, v144, v144, v145
	s_nop 0
	v_max3_f32 v3, v3, v146, v147
	v_mfma_f32_16x16x32_bf16 v[128:131], v[128:131], v[32:35], v[188:191]
	v_max3_f32 v151, v128, v128, v129
	s_nop 0
	v_max3_f32 v151, v151, v130, v131
	v_mfma_f32_16x16x32_bf16 v[140:143], v[136:139], v[16:19], v[120:123]
	v_max3_f32 v3, v3, v140, v141
	s_nop 0
	v_mfma_f32_16x16x32_bf16 v[124:127], v[136:139], v[32:35], v[196:199]
	v_mfma_f32_16x16x32_bf16 v[136:139], v[184:187], v[16:19], v[132:135]
	v_max3_f32 v151, v151, v124, v125
	v_max3_f32 v3, v3, v142, v143
	v_mfma_f32_16x16x32_bf16 v[132:135], v[180:183], v[16:19], v[244:247]
	v_max3_f32 v151, v151, v126, v127
	v_max3_f32 v3, v3, v136, v137
	v_mfma_f32_16x16x32_bf16 v[120:123], v[184:187], v[32:35], v[116:119]
	v_max3_f32 v151, v151, v120, v121
	s_nop 1
	v_mfma_f32_16x16x32_bf16 v[116:119], v[180:183], v[32:35], v[248:251]
	v_max3_f32 v3, v3, v138, v139
	v_max3_f32 v151, v151, v122, v123
	s_nop 0
	v_max3_f32 v3, v3, v132, v133
	v_max3_f32 v151, v151, v116, v117
	v_max3_f32 v3, v3, v134, v135
	s_nop 0
	v_max3_f32 v151, v151, v118, v119
	v_max_f32_e32 v157, v3, v3
	v_max_f32_e32 v153, v151, v151
	v_max_f32_e32 v153, v157, v153
	v_cmp_lt_f32_e32 vcc, s94, v153
	s_cbranch_vccz .LBB0_1007
; template <int MODE, bool DEFER> ...
;     ...
;             m0 = fmaxf(qmax(m0), 0.f); m1 = fmaxf(qmax(m1), 0.f);
;             const float a0 = __builtin_amdgcn_exp2f(-m0), a1 = __builtin_amdgcn_exp2f(-m1);
;             mrun[0] += m0; mrun[1] += m1; lsum[0] *= a0; lsum[1] *= a1;
; #pragma unroll
;             for (int dt = 0; dt < 8; ++dt) { o[0][dt] = o[0][dt] * a0; o[1][dt] = o[1][dt] * a1; }
; #pragma unroll
;             for (int sub = 0; sub < 4; ++sub) { s[0][sub] = s[0][sub] - m0; s[1][sub] = s[1][sub] - m1; }
	v_mov_b32_e32 v153, v3
	s_nop 1
	v_permlane32_swap_b32_e32 v3, v153
	v_max_f32_e32 v153, v153, v153
	v_max_f32_e32 v3, v3, v3
	v_max_f32_e32 v3, v3, v153
	v_mov_b32_e32 v153, v3
	s_nop 1
	v_permlane16_swap_b32_e32 v3, v153
	v_max3_f32 v180, v3, v153, 0
	v_mov_b32_e32 v3, v151
	s_nop 1
	v_permlane32_swap_b32_e32 v151, v3
	v_max_f32_e32 v3, v3, v3
	v_max_f32_e32 v151, v151, v151
	v_max_f32_e32 v3, v151, v3
	v_mov_b32_e32 v151, v3
	s_nop 1
	v_permlane16_swap_b32_e32 v3, v151
	v_max3_f32 v181, v3, v151, 0
	v_exp_f32_e64 v183, -v180
	v_exp_f32_e64 v182, -v181
	v_pk_add_f32 v[170:171], v[170:171], v[180:181]
	v_sub_f32_e32 v144, v144, v180
	v_mov_b32_e32 v184, v183
	v_pk_mul_f32 v[168:169], v[168:169], v[182:183]
	v_pk_mul_f32 v[106:107], v[106:107], v[184:185] op_sel_hi:[1,0]
	v_pk_mul_f32 v[104:105], v[104:105], v[184:185] op_sel_hi:[1,0]
	v_pk_mul_f32 v[82:83], v[82:83], v[182:183] op_sel_hi:[1,0]
	v_pk_mul_f32 v[80:81], v[80:81], v[182:183] op_sel_hi:[1,0]
	v_pk_mul_f32 v[110:111], v[110:111], v[184:185] op_sel_hi:[1,0]
	v_pk_mul_f32 v[108:109], v[108:109], v[184:185] op_sel_hi:[1,0]
	v_pk_mul_f32 v[78:79], v[78:79], v[182:183] op_sel_hi:[1,0]
	v_pk_mul_f32 v[76:77], v[76:77], v[182:183] op_sel_hi:[1,0]
	v_pk_mul_f32 v[102:103], v[102:103], v[184:185] op_sel_hi:[1,0]
	v_pk_mul_f32 v[100:101], v[100:101], v[184:185] op_sel_hi:[1,0]
	v_pk_mul_f32 v[74:75], v[74:75], v[182:183] op_sel_hi:[1,0]
	v_pk_mul_f32 v[72:73], v[72:73], v[182:183] op_sel_hi:[1,0]
	v_pk_mul_f32 v[98:99], v[98:99], v[184:185] op_sel_hi:[1,0]
	v_pk_mul_f32 v[96:97], v[96:97], v[184:185] op_sel_hi:[1,0]
	v_pk_mul_f32 v[70:71], v[70:71], v[182:183] op_sel_hi:[1,0]
	v_pk_mul_f32 v[68:69], v[68:69], v[182:183] op_sel_hi:[1,0]
	v_pk_mul_f32 v[90:91], v[90:91], v[184:185] op_sel_hi:[1,0]
	v_pk_mul_f32 v[88:89], v[88:89], v[184:185] op_sel_hi:[1,0]
	v_pk_mul_f32 v[62:63], v[62:63], v[182:183] op_sel_hi:[1,0]
	v_pk_mul_f32 v[60:61], v[60:61], v[182:183] op_sel_hi:[1,0]
	v_pk_mul_f32 v[86:87], v[86:87], v[184:185] op_sel_hi:[1,0]
	v_pk_mul_f32 v[84:85], v[84:85], v[184:185] op_sel_hi:[1,0]
	v_pk_mul_f32 v[54:55], v[54:55], v[182:183] op_sel_hi:[1,0]
	v_pk_mul_f32 v[52:53], v[52:53], v[182:183] op_sel_hi:[1,0]
	v_pk_mul_f32 v[94:95], v[94:95], v[184:185] op_sel_hi:[1,0]
	v_pk_mul_f32 v[92:93], v[92:93], v[184:185] op_sel_hi:[1,0]
	v_pk_mul_f32 v[66:67], v[66:67], v[182:183] op_sel_hi:[1,0]
	v_pk_mul_f32 v[64:65], v[64:65], v[182:183] op_sel_hi:[1,0]
	v_pk_mul_f32 v[114:115], v[114:115], v[184:185] op_sel_hi:[1,0]
	v_pk_mul_f32 v[112:113], v[112:113], v[184:185] op_sel_hi:[1,0]
	v_pk_mul_f32 v[58:59], v[58:59], v[182:183] op_sel_hi:[1,0]
	v_pk_mul_f32 v[56:57], v[56:57], v[182:183] op_sel_hi:[1,0]
	v_sub_f32_e32 v145, v145, v180
	v_sub_f32_e32 v146, v146, v180
	v_sub_f32_e32 v147, v147, v180
	v_sub_f32_e32 v128, v128, v181
	v_sub_f32_e32 v129, v129, v181
	v_sub_f32_e32 v130, v130, v181
	v_sub_f32_e32 v131, v131, v181
	v_sub_f32_e32 v140, v140, v180
	v_sub_f32_e32 v141, v141, v180
	v_sub_f32_e32 v142, v142, v180
	v_sub_f32_e32 v143, v143, v180
	v_sub_f32_e32 v124, v124, v181
	v_sub_f32_e32 v125, v125, v181
	v_sub_f32_e32 v126, v126, v181
	v_sub_f32_e32 v127, v127, v181
	v_sub_f32_e32 v136, v136, v180
	v_sub_f32_e32 v137, v137, v180
	v_sub_f32_e32 v138, v138, v180
	v_sub_f32_e32 v139, v139, v180
	v_sub_f32_e32 v120, v120, v181
	v_sub_f32_e32 v121, v121, v181
	v_sub_f32_e32 v122, v122, v181
	v_sub_f32_e32 v123, v123, v181
	v_sub_f32_e32 v132, v132, v180
	v_sub_f32_e32 v133, v133, v180
	v_sub_f32_e32 v134, v134, v180
	v_sub_f32_e32 v135, v135, v180
	v_sub_f32_e32 v116, v116, v181
	v_sub_f32_e32 v117, v117, v181
	v_sub_f32_e32 v118, v118, v181
	v_sub_f32_e32 v119, v119, v181
	s_branch .LBB0_1007
